# G1/G4 even phase: the 4 A-tile LDS-DMAs issued in MFMA groups 4..7 instead of 0..3 (late issue); gemm96 early issue kept
# baseline (speedup 1.0000x reference)
.LBB1_56:
	s_mul_i32 s15, s13, 0x4000
	s_add_i32 s15, s15, 16
	s_add_i32 s41, s13, 2
	s_cmp_ge_u32 s41, 3
	s_cselect_b32 s42, 3, 0
	s_sub_i32 s41, s41, s42
	s_mul_i32 s41, s41, 0x4000
	s_add_i32 s41, s41, 16
	s_add_i32 s41, s41, s54
	s_add_i32 s32, s14, 1
	s_min_u32 s32, s32, 15
	s_lshl_b32 s32, s32, 7
	s_add_u32 s50, s18, s32
	s_addc_u32 s51, s19, 0
	s_waitcnt vmcnt(4)
	s_barrier
	v_add_u32_e32 v202, s15, v196
	v_add_u32_e32 v203, s15, v197
	ds_read_b128 v[140:143], v198 offset:0
	ds_read_b128 v[144:147], v198 offset:2048
	ds_read_b128 v[148:151], v198 offset:4096
	ds_read_b128 v[152:155], v198 offset:6144
	ds_read_b128 v[156:159], v202
	ds_read_b128 v[216:219], v199 offset:0
	ds_read_b128 v[220:223], v199 offset:2048
	ds_read_b128 v[224:227], v199 offset:4096
	ds_read_b128 v[228:231], v199 offset:6144
	ds_read_b128 v[188:191], v203
	ds_read_b128 v[192:195], v202 offset:2048
	ds_read_b128 v[208:211], v203 offset:2048
	s_waitcnt lgkmcnt(7)
	v_mfma_f32_16x16x32_bf16 v[124:127], v[140:143], v[156:159], v[124:127]
	v_mfma_f32_16x16x32_bf16 v[120:123], v[144:147], v[156:159], v[120:123]
	v_mfma_f32_16x16x32_bf16 v[116:119], v[148:151], v[156:159], v[116:119]
	v_mfma_f32_16x16x32_bf16 v[112:115], v[152:155], v[156:159], v[112:115]
	ds_read_b128 v[156:159], v202 offset:4096
	s_waitcnt lgkmcnt(3)
	v_mfma_f32_16x16x32_bf16 v[124:127], v[216:219], v[188:191], v[124:127]
	v_mfma_f32_16x16x32_bf16 v[120:123], v[220:223], v[188:191], v[120:123]
	v_mfma_f32_16x16x32_bf16 v[116:119], v[224:227], v[188:191], v[116:119]
	v_mfma_f32_16x16x32_bf16 v[112:115], v[228:231], v[188:191], v[112:115]
	ds_read_b128 v[188:191], v203 offset:4096
	s_waitcnt lgkmcnt(3)
	v_mfma_f32_16x16x32_bf16 v[108:111], v[140:143], v[192:195], v[108:111]
	v_mfma_f32_16x16x32_bf16 v[104:107], v[144:147], v[192:195], v[104:107]
	v_mfma_f32_16x16x32_bf16 v[100:103], v[148:151], v[192:195], v[100:103]
	v_mfma_f32_16x16x32_bf16 v[96:99], v[152:155], v[192:195], v[96:99]
	ds_read_b128 v[192:195], v202 offset:6144
	s_waitcnt lgkmcnt(3)
	v_mfma_f32_16x16x32_bf16 v[108:111], v[216:219], v[208:211], v[108:111]
	v_mfma_f32_16x16x32_bf16 v[104:107], v[220:223], v[208:211], v[104:107]
	v_mfma_f32_16x16x32_bf16 v[100:103], v[224:227], v[208:211], v[100:103]
	v_mfma_f32_16x16x32_bf16 v[96:99], v[228:231], v[208:211], v[96:99]
	ds_read_b128 v[208:211], v203 offset:6144
	s_waitcnt lgkmcnt(3)
	s_add_i32 m0, s41, 0x0
	v_mfma_f32_16x16x32_bf16 v[84:87], v[140:143], v[156:159], v[84:87]
	v_mfma_f32_16x16x32_bf16 v[72:75], v[144:147], v[156:159], v[72:75]
	v_mfma_f32_16x16x32_bf16 v[68:71], v[148:151], v[156:159], v[68:71]
	v_mfma_f32_16x16x32_bf16 v[64:67], v[152:155], v[156:159], v[64:67]
	global_load_lds_dwordx4 v200, s[50:51]
	s_waitcnt lgkmcnt(2)
	s_add_i32 m0, s41, 0x400
	s_add_u32 s52, s50, 0x4000
	s_addc_u32 s53, s51, 0
	v_mfma_f32_16x16x32_bf16 v[84:87], v[216:219], v[188:191], v[84:87]
	v_mfma_f32_16x16x32_bf16 v[72:75], v[220:223], v[188:191], v[72:75]
	v_mfma_f32_16x16x32_bf16 v[68:71], v[224:227], v[188:191], v[68:71]
	v_mfma_f32_16x16x32_bf16 v[64:67], v[228:231], v[188:191], v[64:67]
	global_load_lds_dwordx4 v201, s[52:53]
	s_waitcnt lgkmcnt(1)
	s_add_i32 m0, s41, 0x800
	s_add_u32 s52, s50, 0x8000
	s_addc_u32 s53, s51, 0
	v_mfma_f32_16x16x32_bf16 v[60:63], v[140:143], v[192:195], v[60:63]
	v_mfma_f32_16x16x32_bf16 v[56:59], v[144:147], v[192:195], v[56:59]
	v_mfma_f32_16x16x32_bf16 v[52:55], v[148:151], v[192:195], v[52:55]
	v_mfma_f32_16x16x32_bf16 v[48:51], v[152:155], v[192:195], v[48:51]
	global_load_lds_dwordx4 v200, s[52:53]
	s_waitcnt lgkmcnt(0)
	s_add_i32 m0, s41, 0xc00
	s_add_u32 s52, s50, 0xc000
	s_addc_u32 s53, s51, 0
	v_mfma_f32_16x16x32_bf16 v[60:63], v[216:219], v[208:211], v[60:63]
	v_mfma_f32_16x16x32_bf16 v[56:59], v[220:223], v[208:211], v[56:59]
	v_mfma_f32_16x16x32_bf16 v[52:55], v[224:227], v[208:211], v[52:55]
	v_mfma_f32_16x16x32_bf16 v[48:51], v[228:231], v[208:211], v[48:51]
	global_load_lds_dwordx4 v201, s[52:53]
	s_add_i32 s42, s13, 1
	s_cmp_lg_u32 s13, 2
	s_cselect_b32 s13, s42, 0
	s_mul_i32 s15, s13, 0x4000
	s_add_i32 s15, s15, 16
	s_add_i32 s41, s13, 2
	s_cmp_ge_u32 s41, 3
	s_cselect_b32 s42, 3, 0
	s_sub_i32 s41, s41, s42
	s_mul_i32 s41, s41, 0x4000
	s_add_i32 s41, s41, 16
	s_add_i32 s41, s41, s54
	s_add_u32 s50, s18, s32
	s_addc_u32 s51, s19, 0
	s_add_u32 s50, s50, 0x20000
	s_addc_u32 s51, s51, 0
	s_add_u32 s46, s28, s32
	s_addc_u32 s47, s29, 0
	s_waitcnt vmcnt(4)
	s_barrier
	v_add_u32_e32 v202, s15, v196
	v_add_u32_e32 v203, s15, v197
	ds_read_b128 v[156:159], v202
	ds_read_b128 v[188:191], v203
	ds_read_b128 v[192:195], v202 offset:2048
	ds_read_b128 v[208:211], v203 offset:2048
	s_waitcnt lgkmcnt(3)
	s_add_i32 m0, s54, 0xc010
	v_mfma_f32_16x16x32_bf16 v[44:47], v[140:143], v[156:159], v[44:47]
	v_mfma_f32_16x16x32_bf16 v[40:43], v[144:147], v[156:159], v[40:43]
	v_mfma_f32_16x16x32_bf16 v[36:39], v[148:151], v[156:159], v[36:39]
	v_mfma_f32_16x16x32_bf16 v[32:35], v[152:155], v[156:159], v[32:35]
	ds_read_b128 v[156:159], v202 offset:4096
	global_load_lds_dwordx4 v200, s[46:47]
	s_waitcnt lgkmcnt(3)
	s_add_i32 m0, s54, 0xc410
	s_add_u32 s52, s46, 0x4000
	s_addc_u32 s53, s47, 0
	v_mfma_f32_16x16x32_bf16 v[44:47], v[216:219], v[188:191], v[44:47]
	v_mfma_f32_16x16x32_bf16 v[40:43], v[220:223], v[188:191], v[40:43]
	v_mfma_f32_16x16x32_bf16 v[36:39], v[224:227], v[188:191], v[36:39]
	v_mfma_f32_16x16x32_bf16 v[32:35], v[228:231], v[188:191], v[32:35]
	ds_read_b128 v[188:191], v203 offset:4096
	global_load_lds_dwordx4 v201, s[52:53]
	s_waitcnt lgkmcnt(3)
	s_add_i32 m0, s54, 0xc810
	s_add_u32 s52, s46, 0x8000
	s_addc_u32 s53, s47, 0
	v_mfma_f32_16x16x32_bf16 v[28:31], v[140:143], v[192:195], v[28:31]
	v_mfma_f32_16x16x32_bf16 v[24:27], v[144:147], v[192:195], v[24:27]
	v_mfma_f32_16x16x32_bf16 v[20:23], v[148:151], v[192:195], v[20:23]
	v_mfma_f32_16x16x32_bf16 v[16:19], v[152:155], v[192:195], v[16:19]
	ds_read_b128 v[192:195], v202 offset:6144
	global_load_lds_dwordx4 v200, s[52:53]
	s_waitcnt lgkmcnt(3)
	s_add_i32 m0, s54, 0xcc10
	s_add_u32 s52, s46, 0xc000
	s_addc_u32 s53, s47, 0
	v_mfma_f32_16x16x32_bf16 v[28:31], v[216:219], v[208:211], v[28:31]
	v_mfma_f32_16x16x32_bf16 v[24:27], v[220:223], v[208:211], v[24:27]
	v_mfma_f32_16x16x32_bf16 v[20:23], v[224:227], v[208:211], v[20:23]
	v_mfma_f32_16x16x32_bf16 v[16:19], v[228:231], v[208:211], v[16:19]
	ds_read_b128 v[208:211], v203 offset:6144
	global_load_lds_dwordx4 v201, s[52:53]
	s_waitcnt lgkmcnt(3)
	s_add_i32 m0, s41, 0x0
	v_mfma_f32_16x16x32_bf16 v[12:15], v[140:143], v[156:159], v[12:15]
	v_mfma_f32_16x16x32_bf16 v[8:11], v[144:147], v[156:159], v[8:11]
	v_mfma_f32_16x16x32_bf16 v[4:7], v[148:151], v[156:159], v[4:7]
	v_mfma_f32_16x16x32_bf16 v[0:3], v[152:155], v[156:159], v[0:3]
	global_load_lds_dwordx4 v200, s[50:51]
	s_waitcnt lgkmcnt(2)
	s_add_i32 m0, s41, 0x400
	s_add_u32 s52, s50, 0x4000
	s_addc_u32 s53, s51, 0
	v_mfma_f32_16x16x32_bf16 v[12:15], v[216:219], v[188:191], v[12:15]
	v_mfma_f32_16x16x32_bf16 v[8:11], v[220:223], v[188:191], v[8:11]
	v_mfma_f32_16x16x32_bf16 v[4:7], v[224:227], v[188:191], v[4:7]
	v_mfma_f32_16x16x32_bf16 v[0:3], v[228:231], v[188:191], v[0:3]
	global_load_lds_dwordx4 v201, s[52:53]
	s_waitcnt lgkmcnt(1)
	s_add_i32 m0, s41, 0x800
	s_add_u32 s52, s50, 0x8000
	s_addc_u32 s53, s51, 0
	v_mfma_f32_16x16x32_bf16 v[76:79], v[140:143], v[192:195], v[76:79]
	v_mfma_f32_16x16x32_bf16 v[80:83], v[144:147], v[192:195], v[80:83]
	v_mfma_f32_16x16x32_bf16 v[88:91], v[148:151], v[192:195], v[88:91]
	v_mfma_f32_16x16x32_bf16 v[92:95], v[152:155], v[192:195], v[92:95]
	global_load_lds_dwordx4 v200, s[52:53]
	s_waitcnt lgkmcnt(0)
	s_add_i32 m0, s41, 0xc00
	s_add_u32 s52, s50, 0xc000
	s_addc_u32 s53, s51, 0
	v_mfma_f32_16x16x32_bf16 v[76:79], v[216:219], v[208:211], v[76:79]
	v_mfma_f32_16x16x32_bf16 v[80:83], v[220:223], v[208:211], v[80:83]
	v_mfma_f32_16x16x32_bf16 v[88:91], v[224:227], v[208:211], v[88:91]
	v_mfma_f32_16x16x32_bf16 v[92:95], v[228:231], v[208:211], v[92:95]
	global_load_lds_dwordx4 v201, s[52:53]
	s_add_i32 s42, s13, 1
	s_cmp_lg_u32 s13, 2
	s_cselect_b32 s13, s42, 0
	s_add_i32 s14, s14, 1
	s_cmp_eq_u32 s14, 16
	s_cbranch_scc0 .LBB1_56
	s_setprio 0
	s_cmpk_lt_i32 s7, 0x80
	v_readlane_b32 s10, v242, 5
	s_waitcnt vmcnt(0)
	s_cselect_b64 s[8:9], -1, 0
	v_readlane_b32 s11, v242, 6
	s_and_b64 s[8:9], s[10:11], s[8:9]
	s_mov_b64 s[42:43], -1
	s_and_b64 vcc, exec, s[8:9]
	v_cvt_pk_bf16_f32 v124, v124, v125
	v_cvt_pk_bf16_f32 v125, v126, v127
	v_cvt_pk_bf16_f32 v120, v120, v121
	v_cvt_pk_bf16_f32 v121, v122, v123
	v_cvt_pk_bf16_f32 v116, v116, v117
	v_cvt_pk_bf16_f32 v117, v118, v119
	v_cvt_pk_bf16_f32 v112, v112, v113
	v_cvt_pk_bf16_f32 v113, v114, v115
	v_cvt_pk_bf16_f32 v108, v108, v109
	v_cvt_pk_bf16_f32 v109, v110, v111
	v_cvt_pk_bf16_f32 v104, v104, v105
	v_cvt_pk_bf16_f32 v105, v106, v107
	v_cvt_pk_bf16_f32 v100, v100, v101
	v_cvt_pk_bf16_f32 v101, v102, v103
	v_cvt_pk_bf16_f32 v96, v96, v97
	v_cvt_pk_bf16_f32 v97, v98, v99
	v_cvt_pk_bf16_f32 v84, v84, v85
	v_cvt_pk_bf16_f32 v85, v86, v87
	v_cvt_pk_bf16_f32 v72, v72, v73
	v_cvt_pk_bf16_f32 v73, v74, v75
	v_cvt_pk_bf16_f32 v68, v68, v69
	v_cvt_pk_bf16_f32 v69, v70, v71
	v_cvt_pk_bf16_f32 v64, v64, v65
	v_cvt_pk_bf16_f32 v65, v66, v67
	v_cvt_pk_bf16_f32 v60, v60, v61
	v_cvt_pk_bf16_f32 v61, v62, v63
	v_cvt_pk_bf16_f32 v56, v56, v57
	v_cvt_pk_bf16_f32 v57, v58, v59
	v_cvt_pk_bf16_f32 v52, v52, v53
	v_cvt_pk_bf16_f32 v53, v54, v55
	v_cvt_pk_bf16_f32 v48, v48, v49
	v_cvt_pk_bf16_f32 v49, v50, v51
	v_cvt_pk_bf16_f32 v44, v44, v45
	v_cvt_pk_bf16_f32 v45, v46, v47
	v_cvt_pk_bf16_f32 v40, v40, v41
	v_cvt_pk_bf16_f32 v41, v42, v43
	v_cvt_pk_bf16_f32 v36, v36, v37
	v_cvt_pk_bf16_f32 v37, v38, v39
	v_cvt_pk_bf16_f32 v32, v32, v33
	v_cvt_pk_bf16_f32 v33, v34, v35
	v_cvt_pk_bf16_f32 v28, v28, v29
	v_cvt_pk_bf16_f32 v29, v30, v31
	v_cvt_pk_bf16_f32 v24, v24, v25
	v_cvt_pk_bf16_f32 v25, v26, v27
	v_cvt_pk_bf16_f32 v20, v20, v21
	v_cvt_pk_bf16_f32 v21, v22, v23
	v_cvt_pk_bf16_f32 v16, v16, v17
	v_cvt_pk_bf16_f32 v17, v18, v19
	v_cvt_pk_bf16_f32 v12, v12, v13
	v_cvt_pk_bf16_f32 v13, v14, v15
	v_cvt_pk_bf16_f32 v14, v8, v9
	v_cvt_pk_bf16_f32 v15, v10, v11
	v_cvt_pk_bf16_f32 v8, v4, v5
	v_cvt_pk_bf16_f32 v9, v6, v7
	v_cvt_pk_bf16_f32 v10, v0, v1
	v_cvt_pk_bf16_f32 v11, v2, v3
	v_cvt_pk_bf16_f32 v2, v76, v77
	v_cvt_pk_bf16_f32 v3, v78, v79
	v_cvt_pk_bf16_f32 v6, v80, v81
	v_cvt_pk_bf16_f32 v7, v82, v83
	v_cvt_pk_bf16_f32 v0, v88, v89
	v_cvt_pk_bf16_f32 v1, v90, v91
	v_cvt_pk_bf16_f32 v4, v92, v93
	v_cvt_pk_bf16_f32 v5, v94, v95
	s_waitcnt vmcnt(0)
	s_barrier
	s_cbranch_vccnz .LBB1_59
	s_load_dwordx16 s[64:79], s[0:1], 0x140
	v_or_b32_e32 v18, s4, v135
	v_add_u32_e32 v18, s6, v18
	v_lshl_or_b32 v19, v136, 2, s40
	v_or_b32_e32 v22, s5, v19
	v_ashrrev_i32_e32 v19, 31, v18
	v_lshlrev_b64 v[26:27], 12, v[18:19]
	v_ashrrev_i32_e32 v23, 31, v22
	s_waitcnt lgkmcnt(0)
	v_lshl_add_u64 v[26:27], s[76:77], 0, v[26:27]
	v_lshlrev_b64 v[22:23], 1, v[22:23]
	v_lshl_add_u64 v[26:27], v[26:27], 0, v[22:23]
	global_store_dwordx2 v[26:27], v[124:125], off
	global_store_dwordx2 v[26:27], v[120:121], off offset:32
	global_store_dwordx2 v[26:27], v[116:117], off offset:64
	global_store_dwordx2 v[26:27], v[112:113], off offset:96
	v_or_b32_e32 v26, 16, v18
	v_ashrrev_i32_e32 v27, 31, v26
	v_lshlrev_b64 v[26:27], 12, v[26:27]
	v_lshl_add_u64 v[26:27], s[76:77], 0, v[26:27]
	v_lshl_add_u64 v[26:27], v[26:27], 0, v[22:23]
	global_store_dwordx2 v[26:27], v[108:109], off
	global_store_dwordx2 v[26:27], v[104:105], off offset:32
	global_store_dwordx2 v[26:27], v[100:101], off offset:64
	global_store_dwordx2 v[26:27], v[96:97], off offset:96
	v_or_b32_e32 v26, 32, v18
	v_ashrrev_i32_e32 v27, 31, v26
	v_lshlrev_b64 v[26:27], 12, v[26:27]
	v_lshl_add_u64 v[26:27], s[76:77], 0, v[26:27]
	v_lshl_add_u64 v[26:27], v[26:27], 0, v[22:23]
	global_store_dwordx2 v[26:27], v[84:85], off
	global_store_dwordx2 v[26:27], v[72:73], off offset:32
	global_store_dwordx2 v[26:27], v[68:69], off offset:64
	global_store_dwordx2 v[26:27], v[64:65], off offset:96
	v_or_b32_e32 v26, 48, v18
	v_ashrrev_i32_e32 v27, 31, v26
	v_lshlrev_b64 v[26:27], 12, v[26:27]
	v_lshl_add_u64 v[26:27], s[76:77], 0, v[26:27]
	v_lshl_add_u64 v[26:27], v[26:27], 0, v[22:23]
	global_store_dwordx2 v[26:27], v[60:61], off
	global_store_dwordx2 v[26:27], v[56:57], off offset:32
	global_store_dwordx2 v[26:27], v[52:53], off offset:64
	global_store_dwordx2 v[26:27], v[48:49], off offset:96
	v_or_b32_e32 v26, 64, v18
	v_ashrrev_i32_e32 v27, 31, v26
	v_lshlrev_b64 v[26:27], 12, v[26:27]
	v_lshl_add_u64 v[26:27], s[76:77], 0, v[26:27]
	v_lshl_add_u64 v[26:27], v[26:27], 0, v[22:23]
	global_store_dwordx2 v[26:27], v[44:45], off
	global_store_dwordx2 v[26:27], v[40:41], off offset:32
	global_store_dwordx2 v[26:27], v[36:37], off offset:64
	global_store_dwordx2 v[26:27], v[32:33], off offset:96
	v_or_b32_e32 v26, 0x50, v18
	v_ashrrev_i32_e32 v27, 31, v26
	v_lshlrev_b64 v[26:27], 12, v[26:27]
	v_lshl_add_u64 v[26:27], s[76:77], 0, v[26:27]
	v_lshl_add_u64 v[26:27], v[26:27], 0, v[22:23]
	global_store_dwordx2 v[26:27], v[28:29], off
	global_store_dwordx2 v[26:27], v[24:25], off offset:32
	global_store_dwordx2 v[26:27], v[20:21], off offset:64
	global_store_dwordx2 v[26:27], v[16:17], off offset:96
	v_or_b32_e32 v26, 0x60, v18
	v_ashrrev_i32_e32 v27, 31, v26
	v_lshlrev_b64 v[26:27], 12, v[26:27]
	v_lshl_add_u64 v[26:27], s[76:77], 0, v[26:27]
	v_or_b32_e32 v18, 0x70, v18
	v_lshl_add_u64 v[26:27], v[26:27], 0, v[22:23]
	v_ashrrev_i32_e32 v19, 31, v18
	global_store_dwordx2 v[26:27], v[12:13], off
	global_store_dwordx2 v[26:27], v[14:15], off offset:32
	global_store_dwordx2 v[26:27], v[8:9], off offset:64
	global_store_dwordx2 v[26:27], v[10:11], off offset:96
	v_lshlrev_b64 v[18:19], 12, v[18:19]
	v_lshl_add_u64 v[18:19], s[76:77], 0, v[18:19]
	s_load_dwordx16 s[64:79], s[0:1], 0x100
	v_lshl_add_u64 v[18:19], v[18:19], 0, v[22:23]
	s_mov_b64 s[42:43], 0
	global_store_dwordx2 v[18:19], v[2:3], off
	global_store_dwordx2 v[18:19], v[6:7], off offset:32
	global_store_dwordx2 v[18:19], v[0:1], off offset:64
	global_store_dwordx2 v[18:19], v[4:5], off offset:96

.LBB1_1180:
	s_mul_i32 s15, s13, 0x4000
	s_add_i32 s15, s15, 16
	s_add_i32 s41, s13, 2
	s_cmp_ge_u32 s41, 3
	s_cselect_b32 s42, 3, 0
	s_sub_i32 s41, s41, s42
	s_mul_i32 s41, s41, 0x4000
	s_add_i32 s41, s41, 16
	s_add_i32 s41, s41, s54
	s_add_i32 s32, s14, 1
	s_min_u32 s32, s32, 15
	s_lshl_b32 s32, s32, 7
	s_add_u32 s50, s18, s32
	s_addc_u32 s51, s19, 0
	s_waitcnt vmcnt(4)
	s_barrier
	v_add_u32_e32 v202, s15, v196
	v_add_u32_e32 v203, s15, v197
	ds_read_b128 v[142:145], v198 offset:0
	ds_read_b128 v[146:149], v198 offset:2048
	ds_read_b128 v[150:153], v198 offset:4096
	ds_read_b128 v[154:157], v198 offset:6144
	ds_read_b128 v[158:161], v202
	ds_read_b128 v[216:219], v199 offset:0
	ds_read_b128 v[220:223], v199 offset:2048
	ds_read_b128 v[224:227], v199 offset:4096
	ds_read_b128 v[228:231], v199 offset:6144
	ds_read_b128 v[188:191], v203
	ds_read_b128 v[192:195], v202 offset:2048
	ds_read_b128 v[208:211], v203 offset:2048
	s_waitcnt lgkmcnt(7)
	v_mfma_f32_16x16x32_bf16 v[124:127], v[142:145], v[158:161], v[124:127]
	v_mfma_f32_16x16x32_bf16 v[120:123], v[146:149], v[158:161], v[120:123]
	v_mfma_f32_16x16x32_bf16 v[116:119], v[150:153], v[158:161], v[116:119]
	v_mfma_f32_16x16x32_bf16 v[112:115], v[154:157], v[158:161], v[112:115]
	ds_read_b128 v[158:161], v202 offset:4096
	s_waitcnt lgkmcnt(3)
	v_mfma_f32_16x16x32_bf16 v[124:127], v[216:219], v[188:191], v[124:127]
	v_mfma_f32_16x16x32_bf16 v[120:123], v[220:223], v[188:191], v[120:123]
	v_mfma_f32_16x16x32_bf16 v[116:119], v[224:227], v[188:191], v[116:119]
	v_mfma_f32_16x16x32_bf16 v[112:115], v[228:231], v[188:191], v[112:115]
	ds_read_b128 v[188:191], v203 offset:4096
	s_waitcnt lgkmcnt(3)
	v_mfma_f32_16x16x32_bf16 v[108:111], v[142:145], v[192:195], v[108:111]
	v_mfma_f32_16x16x32_bf16 v[104:107], v[146:149], v[192:195], v[104:107]
	v_mfma_f32_16x16x32_bf16 v[100:103], v[150:153], v[192:195], v[100:103]
	v_mfma_f32_16x16x32_bf16 v[96:99], v[154:157], v[192:195], v[96:99]
	ds_read_b128 v[192:195], v202 offset:6144
	s_waitcnt lgkmcnt(3)
	v_mfma_f32_16x16x32_bf16 v[108:111], v[216:219], v[208:211], v[108:111]
	v_mfma_f32_16x16x32_bf16 v[104:107], v[220:223], v[208:211], v[104:107]
	v_mfma_f32_16x16x32_bf16 v[100:103], v[224:227], v[208:211], v[100:103]
	v_mfma_f32_16x16x32_bf16 v[96:99], v[228:231], v[208:211], v[96:99]
	ds_read_b128 v[208:211], v203 offset:6144
	s_waitcnt lgkmcnt(3)
	s_add_i32 m0, s41, 0x0
	v_mfma_f32_16x16x32_bf16 v[92:95], v[142:145], v[158:161], v[92:95]
	v_mfma_f32_16x16x32_bf16 v[88:91], v[146:149], v[158:161], v[88:91]
	v_mfma_f32_16x16x32_bf16 v[84:87], v[150:153], v[158:161], v[84:87]
	v_mfma_f32_16x16x32_bf16 v[80:83], v[154:157], v[158:161], v[80:83]
	global_load_lds_dwordx4 v200, s[50:51]
	s_waitcnt lgkmcnt(2)
	s_add_i32 m0, s41, 0x400
	s_add_u32 s52, s50, 0x4000
	s_addc_u32 s53, s51, 0
	v_mfma_f32_16x16x32_bf16 v[92:95], v[216:219], v[188:191], v[92:95]
	v_mfma_f32_16x16x32_bf16 v[88:91], v[220:223], v[188:191], v[88:91]
	v_mfma_f32_16x16x32_bf16 v[84:87], v[224:227], v[188:191], v[84:87]
	v_mfma_f32_16x16x32_bf16 v[80:83], v[228:231], v[188:191], v[80:83]
	global_load_lds_dwordx4 v201, s[52:53]
	s_waitcnt lgkmcnt(1)
	s_add_i32 m0, s41, 0x800
	s_add_u32 s52, s50, 0x8000
	s_addc_u32 s53, s51, 0
	v_mfma_f32_16x16x32_bf16 v[76:79], v[142:145], v[192:195], v[76:79]
	v_mfma_f32_16x16x32_bf16 v[72:75], v[146:149], v[192:195], v[72:75]
	v_mfma_f32_16x16x32_bf16 v[68:71], v[150:153], v[192:195], v[68:71]
	v_mfma_f32_16x16x32_bf16 v[48:51], v[154:157], v[192:195], v[48:51]
	global_load_lds_dwordx4 v200, s[52:53]
	s_waitcnt lgkmcnt(0)
	s_add_i32 m0, s41, 0xc00
	s_add_u32 s52, s50, 0xc000
	s_addc_u32 s53, s51, 0
	v_mfma_f32_16x16x32_bf16 v[76:79], v[216:219], v[208:211], v[76:79]
	v_mfma_f32_16x16x32_bf16 v[72:75], v[220:223], v[208:211], v[72:75]
	v_mfma_f32_16x16x32_bf16 v[68:71], v[224:227], v[208:211], v[68:71]
	v_mfma_f32_16x16x32_bf16 v[48:51], v[228:231], v[208:211], v[48:51]
	global_load_lds_dwordx4 v201, s[52:53]
	s_add_i32 s42, s13, 1
	s_cmp_lg_u32 s13, 2
	s_cselect_b32 s13, s42, 0
	s_mul_i32 s15, s13, 0x4000
	s_add_i32 s15, s15, 16
	s_add_i32 s41, s13, 2
	s_cmp_ge_u32 s41, 3
	s_cselect_b32 s42, 3, 0
	s_sub_i32 s41, s41, s42
	s_mul_i32 s41, s41, 0x4000
	s_add_i32 s41, s41, 16
	s_add_i32 s41, s41, s54
	s_add_u32 s50, s18, s32
	s_addc_u32 s51, s19, 0
	s_add_u32 s50, s50, 0x20000
	s_addc_u32 s51, s51, 0
	s_add_u32 s46, s28, s32
	s_addc_u32 s47, s29, 0
	s_waitcnt vmcnt(4)
	s_barrier
	v_add_u32_e32 v202, s15, v196
	v_add_u32_e32 v203, s15, v197
	ds_read_b128 v[158:161], v202
	ds_read_b128 v[188:191], v203
	ds_read_b128 v[192:195], v202 offset:2048
	ds_read_b128 v[208:211], v203 offset:2048
	s_waitcnt lgkmcnt(3)
	s_add_i32 m0, s54, 0xc010
	v_mfma_f32_16x16x32_bf16 v[44:47], v[142:145], v[158:161], v[44:47]
	v_mfma_f32_16x16x32_bf16 v[40:43], v[146:149], v[158:161], v[40:43]
	v_mfma_f32_16x16x32_bf16 v[36:39], v[150:153], v[158:161], v[36:39]
	v_mfma_f32_16x16x32_bf16 v[32:35], v[154:157], v[158:161], v[32:35]
	ds_read_b128 v[158:161], v202 offset:4096
	global_load_lds_dwordx4 v200, s[46:47]
	s_waitcnt lgkmcnt(3)
	s_add_i32 m0, s54, 0xc410
	s_add_u32 s52, s46, 0x4000
	s_addc_u32 s53, s47, 0
	v_mfma_f32_16x16x32_bf16 v[44:47], v[216:219], v[188:191], v[44:47]
	v_mfma_f32_16x16x32_bf16 v[40:43], v[220:223], v[188:191], v[40:43]
	v_mfma_f32_16x16x32_bf16 v[36:39], v[224:227], v[188:191], v[36:39]
	v_mfma_f32_16x16x32_bf16 v[32:35], v[228:231], v[188:191], v[32:35]
	ds_read_b128 v[188:191], v203 offset:4096
	global_load_lds_dwordx4 v201, s[52:53]
	s_waitcnt lgkmcnt(3)
	s_add_i32 m0, s54, 0xc810
	s_add_u32 s52, s46, 0x8000
	s_addc_u32 s53, s47, 0
	v_mfma_f32_16x16x32_bf16 v[28:31], v[142:145], v[192:195], v[28:31]
	v_mfma_f32_16x16x32_bf16 v[24:27], v[146:149], v[192:195], v[24:27]
	v_mfma_f32_16x16x32_bf16 v[20:23], v[150:153], v[192:195], v[20:23]
	v_mfma_f32_16x16x32_bf16 v[16:19], v[154:157], v[192:195], v[16:19]
	ds_read_b128 v[192:195], v202 offset:6144
	global_load_lds_dwordx4 v200, s[52:53]
	s_waitcnt lgkmcnt(3)
	s_add_i32 m0, s54, 0xcc10
	s_add_u32 s52, s46, 0xc000
	s_addc_u32 s53, s47, 0
	v_mfma_f32_16x16x32_bf16 v[28:31], v[216:219], v[208:211], v[28:31]
	v_mfma_f32_16x16x32_bf16 v[24:27], v[220:223], v[208:211], v[24:27]
	v_mfma_f32_16x16x32_bf16 v[20:23], v[224:227], v[208:211], v[20:23]
	v_mfma_f32_16x16x32_bf16 v[16:19], v[228:231], v[208:211], v[16:19]
	ds_read_b128 v[208:211], v203 offset:6144
	global_load_lds_dwordx4 v201, s[52:53]
	s_waitcnt lgkmcnt(3)
	s_add_i32 m0, s41, 0x0
	v_mfma_f32_16x16x32_bf16 v[12:15], v[142:145], v[158:161], v[12:15]
	v_mfma_f32_16x16x32_bf16 v[8:11], v[146:149], v[158:161], v[8:11]
	v_mfma_f32_16x16x32_bf16 v[4:7], v[150:153], v[158:161], v[4:7]
	v_mfma_f32_16x16x32_bf16 v[0:3], v[154:157], v[158:161], v[0:3]
	global_load_lds_dwordx4 v200, s[50:51]
	s_waitcnt lgkmcnt(2)
	s_add_i32 m0, s41, 0x400
	s_add_u32 s52, s50, 0x4000
	s_addc_u32 s53, s51, 0
	v_mfma_f32_16x16x32_bf16 v[12:15], v[216:219], v[188:191], v[12:15]
	v_mfma_f32_16x16x32_bf16 v[8:11], v[220:223], v[188:191], v[8:11]
	v_mfma_f32_16x16x32_bf16 v[4:7], v[224:227], v[188:191], v[4:7]
	v_mfma_f32_16x16x32_bf16 v[0:3], v[228:231], v[188:191], v[0:3]
	global_load_lds_dwordx4 v201, s[52:53]
	s_waitcnt lgkmcnt(1)
	s_add_i32 m0, s41, 0x800
	s_add_u32 s52, s50, 0x8000
	s_addc_u32 s53, s51, 0
	v_mfma_f32_16x16x32_bf16 v[60:63], v[142:145], v[192:195], v[60:63]
	v_mfma_f32_16x16x32_bf16 v[64:67], v[146:149], v[192:195], v[64:67]
	v_mfma_f32_16x16x32_bf16 v[52:55], v[150:153], v[192:195], v[52:55]
	v_mfma_f32_16x16x32_bf16 v[56:59], v[154:157], v[192:195], v[56:59]
	global_load_lds_dwordx4 v200, s[52:53]
	s_waitcnt lgkmcnt(0)
	s_add_i32 m0, s41, 0xc00
	s_add_u32 s52, s50, 0xc000
	s_addc_u32 s53, s51, 0
	v_mfma_f32_16x16x32_bf16 v[60:63], v[216:219], v[208:211], v[60:63]
	v_mfma_f32_16x16x32_bf16 v[64:67], v[220:223], v[208:211], v[64:67]
	v_mfma_f32_16x16x32_bf16 v[52:55], v[224:227], v[208:211], v[52:55]
	v_mfma_f32_16x16x32_bf16 v[56:59], v[228:231], v[208:211], v[56:59]
	global_load_lds_dwordx4 v201, s[52:53]
	s_add_i32 s42, s13, 1
	s_cmp_lg_u32 s13, 2
	s_cselect_b32 s13, s42, 0
	s_add_i32 s14, s14, 1
	s_cmp_eq_u32 s14, 16
	s_cbranch_scc0 .LBB1_1180
	s_setprio 0
	s_waitcnt vmcnt(0)
	s_waitcnt vmcnt(0)
	s_barrier
	s_load_dwordx8 s[80:87], s[0:1], 0x180
	s_cmp_lt_i32 s4, 64
	v_readlane_b32 s12, v242, 9
	s_cselect_b64 s[10:11], -1, 0
	v_readlane_b32 s13, v242, 10
	s_and_b64 s[10:11], s[12:13], s[10:11]
	s_mov_b64 s[38:39], -1
	s_and_b64 vcc, exec, s[10:11]
	s_movk_i32 s12, 0x2020
	s_cbranch_vccnz .LBB1_1291
	v_or_b32_e32 v128, s6, v139
	v_add_u32_e32 v132, s8, v128
	v_lshl_or_b32 v128, v140, 2, s30
	v_or_b32_e32 v130, s7, v128
	v_lshlrev_b32_e32 v134, 5, v132
	s_movk_i32 s8, 0x1fff
	v_ashrrev_i32_e32 v135, 31, v134
	v_cmp_lt_i32_e32 vcc, s8, v130
	s_and_saveexec_b64 s[8:9], vcc
	s_xor_b64 s[40:41], exec, s[8:9]
	s_cbranch_execz .LBB1_1186
	v_cmp_gt_u32_e64 s[38:39], s12, v130
	s_and_saveexec_b64 s[42:43], s[38:39]
	s_cbranch_execz .LBB1_1185
	v_add_u32_e32 v128, 0xffffe000, v130
	v_lshl_add_u64 v[136:137], v[134:135], 2, s[78:79]
	v_lshlrev_b64 v[142:143], 2, v[128:129]
	v_lshl_add_u64 v[136:137], v[136:137], 0, v[142:143]
	v_lshl_add_u64 v[142:143], s[22:23], 0, v[142:143]
	global_load_dwordx4 v[142:145], v[142:143], off
	s_waitcnt vmcnt(0)
	v_pk_add_f32 v[144:145], v[126:127], v[144:145]
	v_pk_add_f32 v[142:143], v[124:125], v[142:143]
	global_store_dwordx4 v[136:137], v[142:145], off
